# FFN-down GEMM residual epilogue at layer 0 rewritten: batched loads, counted waits, stores back to back
# baseline (speedup 1.0000x reference)
;     __device__ __forceinline__ void emit(int row, int pn, int col0, float* v) const {
;     ...
;         case K_WO: case K_DN: {
;             const size_t o = ((size_t)grp * TG + row) * D + col0;
;     __device__ __forceinline__ bool apply(f32x4 (&acc)[2][2][4][2], const pg8::Unit& u, int wr, int wc, int fr, int fq) const {
;         if (kind != K_BR3) { (*this)(acc, u, wr, wc, fr, fq); return false; }
.LBB0_462:
	s_cmp_eq_u32 s28, 3
	s_cbranch_scc1 .Llo_epi
	s_cmp_eq_u32 s28, 5
	s_cbranch_scc1 .Lwo_epi
	s_cmp_eq_u32 s28, 7
	s_cbranch_scc0 .Lfx_no
	v_readlane_b32 s98, v255, 12
	s_cmpk_gt_u32 s98, 24
	s_cbranch_scc1 .Lfn_epi
	s_branch .Ldc_epi

;     __device__ __forceinline__ void emit(int row, int pn, int col0, float* v) const {
;     ...
;         case K_WO: case K_DN: {
;             const size_t o = ((size_t)grp * TG + row) * D + col0;
;             const f32x4 a0 = ldg<f32x4>(xi + o), a1 = ldg<f32x4>(xi + o + 4);
;             f32x4 r0, r1; r0.x = a0.x + v[0]; r0.y = a0.y + v[1]; r0.z = a0.z + v[2]; r0.w = a0.w + v[3]; r1.x = a1.x + v[4]; r1.y = a1.y + v[5]; r1.z = a1.z + v[6]; r1.w = a1.w + v[7];
;             stg<f32x4>(xo + o, r0); stg<f32x4>(xo + o + 4, r1);
;         } break;
;     __device__ __forceinline__ void operator()(const f32x4 (&acc)[2][2][4][2], const pg8::Unit& u, int wr, int wc, int fr, int fq) const {
;         const int row0 = u.pm * 256 + wr * 64 + fr, colb = u.pn * 256 + wc * 32 + 8 * fq;
; #pragma unroll
;         for (int ai = 0; ai < 2; ++ai)
; #pragma unroll
;             for (int m = 0; m < 4; ++m)
; #pragma unroll
;                 for (int bj = 0; bj < 2; ++bj) {
;                     float v[8]; const f32x4 v0 = acc[ai][bj][m][0], v1 = acc[ai][bj][m][1];
;                     v[0] = v0.x; v[1] = v0.y; v[2] = v0.z; v[3] = v0.w; v[4] = v1.x; v[5] = v1.y; v[6] = v1.z; v[7] = v1.w;
;                     emit(row0 + ai * 128 + m * 16, u.pn, colb + bj * 128, v);
;                 }
;     }
.Ldc_epi:
	v_lshl_add_u32 v202, s43, 8, v186
	s_lshl_b32 s98, s42, 8
	v_or_b32_e32 v203, s98, v188
	v_lshl_add_u32 v242, v202, 10, v203
	v_add_u32_e32 v242, s0, v242
	v_lshlrev_b32_e32 v242, 2, v242
	v_mov_b32_e32 v182, v242
	v_add_u32_e32 v183, 0x10000, v242
	v_add_u32_e32 v184, 0x20000, v242
	v_add_u32_e32 v185, 0x30000, v242
	v_add_u32_e32 v190, 0x80000, v242
	v_add_u32_e32 v191, 0x90000, v242
	v_add_u32_e32 v200, 0xa0000, v242
	v_add_u32_e32 v201, 0xb0000, v242
	global_load_dwordx4 v[210:213], v182, s[74:75]
	global_load_dwordx4 v[214:217], v182, s[74:75] offset:16
	global_load_dwordx4 v[218:221], v182, s[74:75] offset:512
	global_load_dwordx4 v[222:225], v182, s[74:75] offset:528
	global_load_dwordx4 v[226:229], v183, s[74:75]
	global_load_dwordx4 v[230:233], v183, s[74:75] offset:16
	global_load_dwordx4 v[234:237], v183, s[74:75] offset:512
	global_load_dwordx4 v[238:241], v183, s[74:75] offset:528
	global_load_dwordx4 v[132:135], v184, s[74:75]
	global_load_dwordx4 v[136:139], v184, s[74:75] offset:16
	global_load_dwordx4 v[140:143], v184, s[74:75] offset:512
	global_load_dwordx4 v[144:147], v184, s[74:75] offset:528
	global_load_dwordx4 v[148:151], v185, s[74:75]
	global_load_dwordx4 v[152:155], v185, s[74:75] offset:16
	global_load_dwordx4 v[156:159], v185, s[74:75] offset:512
	global_load_dwordx4 v[160:163], v185, s[74:75] offset:528
	s_waitcnt vmcnt(8)
	v_pk_add_f32 v[128:129], v[128:129], v[210:211]
	v_pk_add_f32 v[130:131], v[130:131], v[212:213]
	v_pk_add_f32 v[124:125], v[124:125], v[214:215]
	v_pk_add_f32 v[126:127], v[126:127], v[216:217]
	v_pk_add_f32 v[120:121], v[120:121], v[218:219]
	v_pk_add_f32 v[122:123], v[122:123], v[220:221]
	v_pk_add_f32 v[116:117], v[116:117], v[222:223]
	v_pk_add_f32 v[118:119], v[118:119], v[224:225]
	v_pk_add_f32 v[112:113], v[112:113], v[226:227]
	v_pk_add_f32 v[114:115], v[114:115], v[228:229]
	v_pk_add_f32 v[108:109], v[108:109], v[230:231]
	v_pk_add_f32 v[110:111], v[110:111], v[232:233]
	v_pk_add_f32 v[104:105], v[104:105], v[234:235]
	v_pk_add_f32 v[106:107], v[106:107], v[236:237]
	v_pk_add_f32 v[100:101], v[100:101], v[238:239]
	v_pk_add_f32 v[102:103], v[102:103], v[240:241]
	global_load_dwordx4 v[210:213], v190, s[74:75]
	global_load_dwordx4 v[214:217], v190, s[74:75] offset:16
	global_load_dwordx4 v[218:221], v190, s[74:75] offset:512
	global_load_dwordx4 v[222:225], v190, s[74:75] offset:528
	global_load_dwordx4 v[226:229], v191, s[74:75]
	global_load_dwordx4 v[230:233], v191, s[74:75] offset:16
	global_load_dwordx4 v[234:237], v191, s[74:75] offset:512
	global_load_dwordx4 v[238:241], v191, s[74:75] offset:528
	s_waitcnt vmcnt(8)
	v_pk_add_f32 v[96:97], v[96:97], v[132:133]
	v_pk_add_f32 v[98:99], v[98:99], v[134:135]
	v_pk_add_f32 v[92:93], v[92:93], v[136:137]
	v_pk_add_f32 v[94:95], v[94:95], v[138:139]
	v_pk_add_f32 v[88:89], v[88:89], v[140:141]
	v_pk_add_f32 v[90:91], v[90:91], v[142:143]
	v_pk_add_f32 v[84:85], v[84:85], v[144:145]
	v_pk_add_f32 v[86:87], v[86:87], v[146:147]
	v_pk_add_f32 v[80:81], v[80:81], v[148:149]
	v_pk_add_f32 v[82:83], v[82:83], v[150:151]
	v_pk_add_f32 v[76:77], v[76:77], v[152:153]
	v_pk_add_f32 v[78:79], v[78:79], v[154:155]
	v_pk_add_f32 v[72:73], v[72:73], v[156:157]
	v_pk_add_f32 v[74:75], v[74:75], v[158:159]
	v_pk_add_f32 v[68:69], v[68:69], v[160:161]
	v_pk_add_f32 v[70:71], v[70:71], v[162:163]
	global_load_dwordx4 v[132:135], v200, s[74:75]
	global_load_dwordx4 v[136:139], v200, s[74:75] offset:16
	global_load_dwordx4 v[140:143], v200, s[74:75] offset:512
	global_load_dwordx4 v[144:147], v200, s[74:75] offset:528
	global_load_dwordx4 v[148:151], v201, s[74:75]
	global_load_dwordx4 v[152:155], v201, s[74:75] offset:16
	global_load_dwordx4 v[156:159], v201, s[74:75] offset:512
	global_load_dwordx4 v[160:163], v201, s[74:75] offset:528
	s_waitcnt vmcnt(8)
;     __device__ __forceinline__ void emit(int row, int pn, int col0, float* v) const {
;     ...
;         case K_WO: case K_DN: {
;             const size_t o = ((size_t)grp * TG + row) * D + col0;
;             const f32x4 a0 = ldg<f32x4>(xi + o), a1 = ldg<f32x4>(xi + o + 4);
;             f32x4 r0, r1; r0.x = a0.x + v[0]; r0.y = a0.y + v[1]; r0.z = a0.z + v[2]; r0.w = a0.w + v[3]; r1.x = a1.x + v[4]; r1.y = a1.y + v[5]; r1.z = a1.z + v[6]; r1.w = a1.w + v[7];
;             stg<f32x4>(xo + o, r0); stg<f32x4>(xo + o + 4, r1);
;         } break;
;     __device__ __forceinline__ void operator()(const f32x4 (&acc)[2][2][4][2], const pg8::Unit& u, int wr, int wc, int fr, int fq) const {
;         const int row0 = u.pm * 256 + wr * 64 + fr, colb = u.pn * 256 + wc * 32 + 8 * fq;
; #pragma unroll
;         for (int ai = 0; ai < 2; ++ai)
; #pragma unroll
;             for (int m = 0; m < 4; ++m)
; #pragma unroll
;                 for (int bj = 0; bj < 2; ++bj) {
;                     float v[8]; const f32x4 v0 = acc[ai][bj][m][0], v1 = acc[ai][bj][m][1];
;                     v[0] = v0.x; v[1] = v0.y; v[2] = v0.z; v[3] = v0.w; v[4] = v1.x; v[5] = v1.y; v[6] = v1.z; v[7] = v1.w;
;                     emit(row0 + ai * 128 + m * 16, u.pn, colb + bj * 128, v);
;                 }
;     }
	v_pk_add_f32 v[64:65], v[64:65], v[210:211]
	v_pk_add_f32 v[66:67], v[66:67], v[212:213]
	v_pk_add_f32 v[60:61], v[60:61], v[214:215]
	v_pk_add_f32 v[62:63], v[62:63], v[216:217]
	v_pk_add_f32 v[56:57], v[56:57], v[218:219]
	v_pk_add_f32 v[58:59], v[58:59], v[220:221]
	v_pk_add_f32 v[52:53], v[52:53], v[222:223]
	v_pk_add_f32 v[54:55], v[54:55], v[224:225]
	v_pk_add_f32 v[48:49], v[48:49], v[226:227]
	v_pk_add_f32 v[50:51], v[50:51], v[228:229]
	v_pk_add_f32 v[44:45], v[44:45], v[230:231]
	v_pk_add_f32 v[46:47], v[46:47], v[232:233]
	v_pk_add_f32 v[40:41], v[40:41], v[234:235]
	v_pk_add_f32 v[42:43], v[42:43], v[236:237]
	v_pk_add_f32 v[36:37], v[36:37], v[238:239]
	v_pk_add_f32 v[38:39], v[38:39], v[240:241]
	s_waitcnt vmcnt(0)
	v_pk_add_f32 v[32:33], v[32:33], v[132:133]
	v_pk_add_f32 v[34:35], v[34:35], v[134:135]
	v_pk_add_f32 v[28:29], v[28:29], v[136:137]
	v_pk_add_f32 v[30:31], v[30:31], v[138:139]
	v_pk_add_f32 v[24:25], v[24:25], v[140:141]
	v_pk_add_f32 v[26:27], v[26:27], v[142:143]
	v_pk_add_f32 v[20:21], v[20:21], v[144:145]
	v_pk_add_f32 v[22:23], v[22:23], v[146:147]
	v_pk_add_f32 v[16:17], v[16:17], v[148:149]
	v_pk_add_f32 v[18:19], v[18:19], v[150:151]
	v_pk_add_f32 v[12:13], v[12:13], v[152:153]
	v_pk_add_f32 v[14:15], v[14:15], v[154:155]
	v_pk_add_f32 v[8:9], v[8:9], v[156:157]
	v_pk_add_f32 v[10:11], v[10:11], v[158:159]
	v_pk_add_f32 v[4:5], v[4:5], v[160:161]
	v_pk_add_f32 v[6:7], v[6:7], v[162:163]
	global_store_dwordx4 v182, v[128:131], s[66:67]
	global_store_dwordx4 v182, v[124:127], s[66:67] offset:16
	global_store_dwordx4 v182, v[120:123], s[66:67] offset:512
	global_store_dwordx4 v182, v[116:119], s[66:67] offset:528
	global_store_dwordx4 v183, v[112:115], s[66:67]
	global_store_dwordx4 v183, v[108:111], s[66:67] offset:16
	global_store_dwordx4 v183, v[104:107], s[66:67] offset:512
	global_store_dwordx4 v183, v[100:103], s[66:67] offset:528
	global_store_dwordx4 v184, v[96:99], s[66:67]
	global_store_dwordx4 v184, v[92:95], s[66:67] offset:16
	global_store_dwordx4 v184, v[88:91], s[66:67] offset:512
	global_store_dwordx4 v184, v[84:87], s[66:67] offset:528
	global_store_dwordx4 v185, v[80:83], s[66:67]
	global_store_dwordx4 v185, v[76:79], s[66:67] offset:16
	global_store_dwordx4 v185, v[72:75], s[66:67] offset:512
	global_store_dwordx4 v185, v[68:71], s[66:67] offset:528
	global_store_dwordx4 v190, v[64:67], s[66:67]
	global_store_dwordx4 v190, v[60:63], s[66:67] offset:16
	global_store_dwordx4 v190, v[56:59], s[66:67] offset:512
	global_store_dwordx4 v190, v[52:55], s[66:67] offset:528
	global_store_dwordx4 v191, v[48:51], s[66:67]
	global_store_dwordx4 v191, v[44:47], s[66:67] offset:16
	global_store_dwordx4 v191, v[40:43], s[66:67] offset:512
	global_store_dwordx4 v191, v[36:39], s[66:67] offset:528
	global_store_dwordx4 v200, v[32:35], s[66:67]
	global_store_dwordx4 v200, v[28:31], s[66:67] offset:16
	global_store_dwordx4 v200, v[24:27], s[66:67] offset:512
	global_store_dwordx4 v200, v[20:23], s[66:67] offset:528
	global_store_dwordx4 v201, v[16:19], s[66:67]
	global_store_dwordx4 v201, v[12:15], s[66:67] offset:16
	global_store_dwordx4 v201, v[8:11], s[66:67] offset:512
	global_store_dwordx4 v201, v[4:7], s[66:67] offset:528
	s_branch .LBB0_1375
